# gdn_norm phase: the 256 waves that merge the sample rows split-KV partials take no prompt rows (rows re-dealt over the other waves)
# speedup vs baseline: 1.0584x; 1.0066x over previous
; #define AIN(i) ld_ptr(c.la + 2 * (i))
; __device__ __forceinline__ void p4b_gdn_norm(const Ctx& c0, int l) {
;     ...
;     const int gw = c.bid * 8 + c.wave, NGW = c.G * 8, lane = c.lane;
;     const float* OG = (const float*)(AWS + WS_OG); const bf16* H = (const bf16*)(AWS + WS_H); bf16* MIX = (bf16*)(AWS + WS_MIX);
;     const float nw = ((const float*)AIN(I_GNW))[l * 64 + lane];
;     for (int bn = gw; bn < DB * 2; bn += NGW) sample_combine(c, l, bn, lane);
;     for (int it0 = gw; it0 < MPR * 8; it0 += 8 * NGW) {
.LBB0_1526:
	s_movk_i32 s33, 0x4000
	s_cmp_gt_i32 s12, 0x3fff
	s_cbranch_scc1 .LBB0_1462
	v_readlane_b32 s2, v253, 3
	s_lshl_b32 s2, s2, 3
	s_cmpk_le_u32 s2, 0x200
	s_cbranch_scc1 .Lgn3_map
	s_cmpk_lt_i32 s12, 0x100
	s_cbranch_scc1 .LBB0_1462
	s_sub_i32 s12, s12, 0x100
	s_sub_i32 s2, s2, 0x100
.Lgn3_map:
	s_add_u32 s4, s23, 0x3a900000
	s_addc_u32 s5, s24, 0
	s_add_u32 s6, s13, 0xfd01600
	s_addc_u32 s7, s18, 0
	s_add_u32 s8, s19, 0x20700400
	s_addc_u32 s9, s22, 0
	s_mov_b32 s3, 0x7060302
	v_lshlrev_b32_e32 v40, 5, v18
	v_lshlrev_b32_e32 v41, 4, v18
	v_and_b32_e32 v50, 7, v18
	v_lshlrev_b32_e32 v50, 5, v50
	s_waitcnt vmcnt(0)
	ds_bpermute_b32 v42, v50, v36 offset:0
	ds_bpermute_b32 v43, v50, v36 offset:4
	ds_bpermute_b32 v44, v50, v36 offset:8
	ds_bpermute_b32 v45, v50, v36 offset:12
	ds_bpermute_b32 v46, v50, v36 offset:16
	ds_bpermute_b32 v47, v50, v36 offset:20
	ds_bpermute_b32 v48, v50, v36 offset:24
	ds_bpermute_b32 v49, v50, v36 offset:28
	s_waitcnt lgkmcnt(0)
